# row_pass generic slab loop: 4 partial-slab loads per slab issued together with counted vmcnt (was load-wait x4)
# speedup vs baseline: 1.0039x; 1.0039x over previous
; __device__ __forceinline__ void row_pass(const Params& p, int mode, float coef, const float* nw, int nsplit) {
;     ...
;                 for (int ks = 0; ks < nsplit; ++ks) {
; #pragma unroll
;                     for (int j = 0; j < 4; ++j) fv[j] += __builtin_nontemporal_load(P4 + (size_t)ks * 262144 + 64 * j + lane); } }
.LBB0_1457:
	v_lshl_add_u64 v[50:51], v[44:45], 0, s[16:17]
	s_mov_b32 s20, 0x33b27000
	v_add_co_u32_e32 v54, vcc, s20, v50
	s_add_u32 s16, s16, 0x400000
	s_nop 0
	v_addc_co_u32_e32 v55, vcc, 0, v51, vcc
	s_nop 0
	global_load_dwordx4 v[50:53], v[54:55], off nt
	global_load_dwordx4 v[140:143], v[54:55], off offset:1024 nt
	global_load_dwordx4 v[144:147], v[54:55], off offset:2048 nt
	global_load_dwordx4 v[148:151], v[54:55], off offset:3072 nt
	s_addc_u32 s17, s17, 0
	s_cmp_lg_u32 s19, s16
	s_waitcnt vmcnt(3)
	v_pk_add_f32 v[40:41], v[40:41], v[52:53]
	v_pk_add_f32 v[38:39], v[38:39], v[50:51]
	s_waitcnt vmcnt(2)
	v_pk_add_f32 v[36:37], v[36:37], v[142:143]
	v_pk_add_f32 v[34:35], v[34:35], v[140:141]
	s_waitcnt vmcnt(1)
	v_pk_add_f32 v[28:29], v[28:29], v[146:147]
	v_pk_add_f32 v[2:3], v[2:3], v[144:145]
	s_waitcnt vmcnt(0)
	v_pk_add_f32 v[26:27], v[26:27], v[150:151]
	v_pk_add_f32 v[24:25], v[24:25], v[148:149]
	s_cbranch_scc1 .LBB0_1457
